# adds NA-lat K-fragment LDS reads issued together with counted lgkmcnt
# baseline (speedup 1.0000x reference)
.LBB0_180:
	s_and_b64 vcc, exec, s[0:1]
	s_cbranch_vccz .LBB0_216
	s_cmp_ge_u32 s15, s8
	s_cselect_b64 s[0:1], -1, 0
	s_cmp_lt_u32 s15, s11
	s_cselect_b64 s[18:19], -1, 0
	s_and_b64 s[0:1], s[0:1], s[18:19]
	s_andn2_b64 vcc, exec, s[0:1]
	s_cbranch_vccnz .LBB0_217
	v_add_u32_e32 v14, v14, v148
	ds_read_b128 v[10:13], v14
	ds_read_b128 v[202:205], v14 offset:32
	ds_read_b128 v[206:209], v14 offset:64
	ds_read_b128 v[210:213], v14 offset:96
	v_cmp_lt_u32_e32 vcc, s15, v145
	v_cmp_ge_u32_e64 s[0:1], s15, v150
	s_or_b64 s[0:1], vcc, s[0:1]
	s_or_b64 s[18:19], s[0:1], s[72:73]
	s_nor_b64 s[18:19], s[18:19], s[74:75]
	v_mov_b32_e32 v64, 0xf149f2ca
	s_waitcnt lgkmcnt(3)
	v_mfma_f32_32x32x16_bf16 v[48:63], v[10:13], v[80:83], 0
	s_waitcnt lgkmcnt(2)
	v_mfma_f32_32x32x16_bf16 v[48:63], v[202:205], v[84:87], v[48:63]
	s_waitcnt lgkmcnt(1)
	v_mfma_f32_32x32x16_bf16 v[48:63], v[206:209], v[88:91], v[48:63]
	v_mov_b32_e32 v14, 0xf149f2ca
	s_waitcnt lgkmcnt(0)
	v_mfma_f32_32x32x16_bf16 v[48:63], v[210:213], v[92:95], v[48:63]
	ds_read_b32 v201, v152
	ds_read_b32 v202, v152 offset:4
	ds_read_b32 v203, v152 offset:8
	ds_read_b32 v204, v152 offset:12
	ds_read_b32 v205, v152 offset:32
	ds_read_b32 v206, v152 offset:36
	ds_read_b32 v207, v152 offset:40
	ds_read_b32 v208, v152 offset:44
	ds_read_b32 v209, v152 offset:64
	ds_read_b32 v210, v152 offset:68
	ds_read_b32 v211, v152 offset:72
	ds_read_b32 v212, v152 offset:76
	ds_read_b32 v213, v152 offset:96
	ds_read_b32 v214, v152 offset:100
	ds_read_b32 v215, v152 offset:104
	ds_read_b32 v216, v152 offset:108
	v_mov_b32_e32 v217, 0xf149f2ca
	s_waitcnt lgkmcnt(12)
	v_add_f32_e32 v201, v48, v201
	s_mov_b64 vcc, s[18:19]
	v_sub_f32_e32 v201, v201, v15
	v_cndmask_b32_e32 v64, v217, v201, vcc
	v_add_f32_e32 v202, v49, v202
	s_nor_b64 vcc, s[0:1], s[2:3]
	v_sub_f32_e32 v202, v202, v15
	v_cndmask_b32_e32 v14, v217, v202, vcc
	v_add_f32_e32 v203, v50, v203
	s_nor_b64 vcc, s[0:1], s[22:23]
	v_sub_f32_e32 v203, v203, v15
	v_cndmask_b32_e32 v66, v217, v203, vcc
	v_add_f32_e32 v204, v51, v204
	s_nor_b64 vcc, s[0:1], s[24:25]
	v_sub_f32_e32 v204, v204, v15
	v_cndmask_b32_e32 v65, v217, v204, vcc
	s_waitcnt lgkmcnt(8)
	v_add_f32_e32 v205, v52, v205
	s_nor_b64 vcc, s[0:1], s[30:31]
	v_sub_f32_e32 v205, v205, v15
	v_cndmask_b32_e32 v68, v217, v205, vcc
	v_add_f32_e32 v206, v53, v206
	s_nor_b64 vcc, s[0:1], s[34:35]
	v_sub_f32_e32 v206, v206, v15
	v_cndmask_b32_e32 v67, v217, v206, vcc
	v_add_f32_e32 v207, v54, v207
	s_nor_b64 vcc, s[0:1], s[40:41]
	v_sub_f32_e32 v207, v207, v15
	v_cndmask_b32_e32 v70, v217, v207, vcc
	v_add_f32_e32 v208, v55, v208
	s_nor_b64 vcc, s[0:1], s[42:43]
	v_sub_f32_e32 v208, v208, v15
	v_cndmask_b32_e32 v69, v217, v208, vcc
	s_waitcnt lgkmcnt(4)
	v_add_f32_e32 v209, v56, v209
	s_nor_b64 vcc, s[0:1], s[94:95]
	v_sub_f32_e32 v209, v209, v15
	v_cndmask_b32_e32 v72, v217, v209, vcc
	v_add_f32_e32 v210, v57, v210
	s_nor_b64 vcc, s[0:1], s[38:39]
	v_sub_f32_e32 v210, v210, v15
	v_cndmask_b32_e32 v71, v217, v210, vcc
	v_add_f32_e32 v211, v58, v211
	s_nor_b64 vcc, s[0:1], s[36:37]
	v_sub_f32_e32 v211, v211, v15
	v_cndmask_b32_e32 v74, v217, v211, vcc
	v_add_f32_e32 v212, v59, v212
	s_nor_b64 vcc, s[0:1], s[50:51]
	v_sub_f32_e32 v212, v212, v15
	v_cndmask_b32_e32 v73, v217, v212, vcc
	s_waitcnt lgkmcnt(0)
	v_add_f32_e32 v213, v60, v213
	s_nor_b64 vcc, s[0:1], s[76:77]
	v_sub_f32_e32 v213, v213, v15
	v_cndmask_b32_e32 v76, v217, v213, vcc
	v_add_f32_e32 v214, v61, v214
	s_nor_b64 vcc, s[0:1], s[78:79]
	v_sub_f32_e32 v214, v214, v15
	v_cndmask_b32_e32 v75, v217, v214, vcc
	v_add_f32_e32 v215, v62, v215
	s_nor_b64 vcc, s[0:1], s[80:81]
	v_sub_f32_e32 v215, v215, v15
	v_cndmask_b32_e32 v78, v217, v215, vcc
	v_add_f32_e32 v216, v63, v216
	s_nor_b64 vcc, s[0:1], s[44:45]
	v_sub_f32_e32 v216, v216, v15
	v_cndmask_b32_e32 v77, v217, v216, vcc
	v_exp_f32_e32 v10, v64
	v_exp_f32_e32 v11, v14
	v_exp_f32_e32 v12, v66
	v_exp_f32_e32 v13, v65
	v_exp_f32_e32 v48, v68
	v_exp_f32_e32 v49, v67
	v_exp_f32_e32 v50, v70
	v_exp_f32_e32 v51, v69
	v_pk_add_f32 v[52:53], v[10:11], 0 op_sel_hi:[1,0]
	v_exp_f32_e32 v54, v74
	v_pk_add_f32 v[52:53], v[52:53], v[12:13]
	v_exp_f32_e32 v55, v73
	v_pk_add_f32 v[52:53], v[52:53], v[48:49]
	v_exp_f32_e32 v56, v76
	v_pk_add_f32 v[60:61], v[52:53], v[50:51]
	v_exp_f32_e32 v52, v72
	v_exp_f32_e32 v53, v71
	v_exp_f32_e32 v57, v75
	v_exp_f32_e32 v58, v78
	v_exp_f32_e32 v59, v77
	v_pk_add_f32 v[60:61], v[60:61], v[52:53]
	s_mov_b32 s0, 0x47800000
	v_pk_add_f32 v[60:61], v[60:61], v[54:55]
	s_nop 0
	v_pk_add_f32 v[60:61], v[60:61], v[56:57]
	s_nop 0
	v_pk_add_f32 v[60:61], v[60:61], v[58:59]
	s_nop 0
	v_pk_add_f32 v[60:61], v[60:61], v[60:61] op_sel:[0,1] op_sel_hi:[1,0]
	s_nop 0
	v_cmp_nge_f32_e32 vcc, s0, v60
	v_cmp_eq_u16_sdwa s[0:1], v153, v1 src0_sel:BYTE_0 src1_sel:DWORD
	s_or_b64 vcc, vcc, s[0:1]
	s_cbranch_vccz .LBB0_221
	v_max_f32_e32 v10, v14, v14
	v_max_f32_e32 v11, v64, v64
	v_max_f32_e32 v10, v11, v10
	v_max3_f32 v10, v10, v66, v65
	v_max3_f32 v10, v10, v68, v67
	v_max3_f32 v10, v10, v70, v69
	v_and_b32_e32 v12, 64, v220
	v_max3_f32 v10, v10, v72, v71
	v_xor_b32_e32 v11, 32, v220
	v_add_u32_e32 v12, 64, v12
	v_max3_f32 v10, v10, v74, v73
	v_cmp_lt_i32_e32 vcc, v11, v12
	v_max3_f32 v10, v10, v76, v75
	v_max3_f32 v10, v10, v78, v77
	v_cndmask_b32_e32 v11, v220, v11, vcc
	v_lshlrev_b32_e32 v11, 2, v11
	ds_bpermute_b32 v11, v11, v10
	s_mov_b32 s0, 0xefa18f08
	s_waitcnt lgkmcnt(0)
	v_max_f32_e32 v11, v11, v11
	v_max_f32_e32 v10, v10, v11
	v_and_b32_e32 v11, 1, v153
	v_cmp_lt_f32_e32 vcc, s0, v10
	v_max_f32_e32 v12, 0, v10
	v_cmp_eq_u32_e64 s[0:1], 1, v11
	v_cndmask_b32_e32 v10, 0, v10, vcc
	s_nop 0
	v_cndmask_b32_e64 v61, v10, v12, s[0:1]
	v_exp_f32_e64 v10, -v61
	v_sub_f32_e32 v12, v66, v61
	v_sub_f32_e32 v13, v65, v61
	v_exp_f32_e32 v12, v12
	v_cndmask_b32_e64 v10, 1.0, v10, s[0:1]
	v_mul_f32_e32 v151, v151, v10
	v_pk_mul_f32 v[30:31], v[30:31], v[10:11] op_sel_hi:[1,0]
	v_pk_mul_f32 v[28:29], v[28:29], v[10:11] op_sel_hi:[1,0]
	v_pk_mul_f32 v[26:27], v[26:27], v[10:11] op_sel_hi:[1,0]
	v_pk_mul_f32 v[24:25], v[24:25], v[10:11] op_sel_hi:[1,0]
	v_pk_mul_f32 v[22:23], v[22:23], v[10:11] op_sel_hi:[1,0]
	v_pk_mul_f32 v[20:21], v[20:21], v[10:11] op_sel_hi:[1,0]
	v_pk_mul_f32 v[18:19], v[18:19], v[10:11] op_sel_hi:[1,0]
	v_pk_mul_f32 v[16:17], v[16:17], v[10:11] op_sel_hi:[1,0]
	v_pk_mul_f32 v[46:47], v[46:47], v[10:11] op_sel_hi:[1,0]
	v_pk_mul_f32 v[44:45], v[44:45], v[10:11] op_sel_hi:[1,0]
	v_pk_mul_f32 v[42:43], v[42:43], v[10:11] op_sel_hi:[1,0]
	v_pk_mul_f32 v[40:41], v[40:41], v[10:11] op_sel_hi:[1,0]
	v_pk_mul_f32 v[38:39], v[38:39], v[10:11] op_sel_hi:[1,0]
	v_pk_mul_f32 v[36:37], v[36:37], v[10:11] op_sel_hi:[1,0]
	v_pk_mul_f32 v[34:35], v[34:35], v[10:11] op_sel_hi:[1,0]
	v_pk_mul_f32 v[32:33], v[32:33], v[10:11] op_sel_hi:[1,0]
	v_sub_f32_e32 v10, v64, v61
	v_sub_f32_e32 v11, v14, v61
	v_sub_f32_e32 v14, v68, v61
	v_exp_f32_e32 v10, v10
	v_exp_f32_e32 v11, v11
	v_exp_f32_e32 v48, v14
	v_sub_f32_e32 v14, v67, v61
	v_exp_f32_e32 v13, v13
	v_exp_f32_e32 v49, v14
	v_sub_f32_e32 v14, v70, v61
	v_exp_f32_e32 v50, v14
	v_sub_f32_e32 v14, v69, v61
	v_exp_f32_e32 v51, v14
	v_pk_add_f32 v[52:53], v[10:11], 0 op_sel_hi:[1,0]
	v_sub_f32_e32 v14, v72, v61
	v_pk_add_f32 v[52:53], v[12:13], v[52:53]
	s_or_b64 s[0:1], vcc, s[0:1]
	v_pk_add_f32 v[52:53], v[48:49], v[52:53]
	v_cndmask_b32_e64 v153, 0, 1, s[0:1]
	v_pk_add_f32 v[62:63], v[50:51], v[52:53]
	v_exp_f32_e32 v52, v14
	v_sub_f32_e32 v14, v71, v61
	v_exp_f32_e32 v53, v14
	v_sub_f32_e32 v14, v74, v61
	v_exp_f32_e32 v54, v14
	v_sub_f32_e32 v14, v73, v61
	v_exp_f32_e32 v55, v14
	v_sub_f32_e32 v14, v76, v61
	v_exp_f32_e32 v56, v14
	v_sub_f32_e32 v14, v75, v61
	v_exp_f32_e32 v57, v14
	v_sub_f32_e32 v14, v78, v61
	v_exp_f32_e32 v58, v14
	v_sub_f32_e32 v14, v77, v61
	v_exp_f32_e32 v59, v14
	v_pk_add_f32 v[62:63], v[52:53], v[62:63]
	s_nop 0
	v_pk_add_f32 v[62:63], v[54:55], v[62:63]
	s_nop 0
	v_pk_add_f32 v[62:63], v[56:57], v[62:63]
	s_nop 0
	v_pk_add_f32 v[62:63], v[58:59], v[62:63]
	s_nop 0
	v_mov_b32_e32 v14, v62
	v_mov_b32_e32 v60, v63
	v_pk_add_f32 v[14:15], v[14:15], v[60:61]
	s_branch .LBB0_222
